# compress stage-1: rolling weight pipeline over MFMA-tiled W1 layout + per-task token-line prefetch
# speedup vs baseline: 1.2155x; 1.0204x over previous
; __device__ __forceinline__ unsigned cvt_pk_bf16(float lo, float hi) { const f32x2_t f = {lo, hi}; return __builtin_bit_cast(unsigned, __builtin_convertvector(f, bf16x2_t)); }
; __device__ __forceinline__ void tr_tile(const float* __restrict__ src, int K, int N, bf16_t* __restrict__ dst, bool remap, int kt, int nt, float* sm) {
;     ...
;     const int nl = tid >> 2, kc = (tid & 3) * 16, n = nt * 64 + nl;
;     if (n < N) {
;         const int rr = remap ? nsa_in_rowmap(n) : n;
;         unsigned pk[8];
; #pragma unroll
;         for (int i = 0; i < 8; ++i) pk[i] = cvt_pk_bf16(sm[(kc + 2 * i) * 65 + nl], sm[(kc + 2 * i + 1) * 65 + nl]);
;         bf16_t* dp = dst + (size_t)rr * K + kt * 64 + kc;
;         *(u32x4*)dp = (u32x4){pk[0], pk[1], pk[2], pk[3]};
;         *(u32x4*)(dp + 8) = (u32x4){pk[4], pk[5], pk[6], pk[7]};
;     }
.LBB0_25:
	s_or_b64 exec, exec, s[34:35]
	ds_read2_b32 v[2:3], v18 offset1:65
	ds_read2_b32 v[4:5], v18 offset0:130 offset1:195
	ds_read2_b32 v[6:7], v27 offset0:134 offset1:199
	s_ashr_i32 s41, s40, 31
	s_waitcnt lgkmcnt(2)
	v_cvt_pk_bf16_f32 v2, v2, v3
	s_waitcnt lgkmcnt(1)
	v_cvt_pk_bf16_f32 v3, v4, v5
	ds_read2_b32 v[4:5], v27 offset0:4 offset1:69
	s_waitcnt lgkmcnt(0)
	v_cvt_pk_bf16_f32 v4, v4, v5
	v_cvt_pk_bf16_f32 v5, v6, v7
	ds_read2_b32 v[6:7], v28 offset0:8 offset1:73
	s_waitcnt lgkmcnt(0)
	v_cvt_pk_bf16_f32 v34, v6, v7
	ds_read2_b32 v[6:7], v28 offset0:138 offset1:203
	s_waitcnt lgkmcnt(0)
	v_cvt_pk_bf16_f32 v35, v6, v7
	ds_read2_b32 v[6:7], v29 offset0:12 offset1:77
	s_waitcnt lgkmcnt(0)
	v_cvt_pk_bf16_f32 v36, v6, v7
	ds_read2_b32 v[6:7], v29 offset0:142 offset1:207
	s_waitcnt lgkmcnt(0)
	v_cvt_pk_bf16_f32 v37, v6, v7
	s_cmpk_eq_u32 s49, 0x800
	s_cbranch_scc0 .Lpro_rowmajor
	v_lshrrev_b32_e32 v246, 4, v0
	v_lshlrev_b32_e32 v246, 16, v246
	v_and_b32_e32 v247, 15, v0
	v_lshl_or_b32 v246, v247, 4, v246
	v_lshrrev_b32_e32 v247, 6, v8
	v_lshl_or_b32 v246, v247, 10, v246
	v_and_b32_e32 v247, 32, v8
	v_lshl_or_b32 v246, v247, 4, v246
	s_lshr_b32 s34, s40, 5
	s_lshl_b32 s34, s34, 10
	v_add_u32_e32 v246, s34, v246
	v_mov_b32_e32 v247, 0
	v_lshl_add_u64 v[246:247], s[36:37], 0, v[246:247]
	global_store_dwordx4 v[246:247], v[2:5], off
	global_store_dwordx4 v[246:247], v[34:37], off offset:256
	s_branch .LBB0_26
.Lpro_rowmajor:
	v_ashrrev_i32_e32 v7, 31, v0
	v_mad_u64_u32 v[0:1], s[34:35], v0, s49, 0
	v_mov_b32_e32 v6, v1
	v_mad_u64_u32 v[6:7], s[34:35], v7, s49, v[6:7]
	v_mov_b32_e32 v1, v6
	v_lshl_add_u64 v[0:1], v[0:1], 1, s[36:37]
	v_lshl_add_u64 v[0:1], s[40:41], 1, v[0:1]
	v_lshl_add_u64 v[0:1], v[0:1], 0, v[8:9]
	global_store_dwordx4 v[0:1], v[2:5], off
	global_store_dwordx4 v[0:1], v[34:37], off offset:16

; __device__ __forceinline__ unsigned cvt_pk_bf16(float lo, float hi) { const f32x2_t f = {lo, hi}; return __builtin_bit_cast(unsigned, __builtin_convertvector(f, bf16x2_t)); }
; __device__ __forceinline__ float bf_lo(unsigned u) { return __uint_as_float(u << 16); }
; __device__ __forceinline__ float bf_hi(unsigned u) { return __uint_as_float(u & 0xffff0000u); }
; __device__ __forceinline__ f32x4 mfma16(bf16x8 a, bf16x8 b, f32x4 c) { return __builtin_amdgcn_mfma_f32_16x16x32_bf16(a, b, c, 0, 0, 0); }
; __device__ __forceinline__ void compress_task(const Params& p, int task, char* smem) {
;     ...
;     const int n = n0 + fr;
; #pragma unroll 2
;     for (int kq = 0; kq < 16; ++kq) {
;         const int kk = w * 16 + kq, l = kk >> 1, d = (kk & 1) * 32 + fq * 8;
;         int tok = 16 * n + l; tok = tok < S ? tok : S - 1;
;         const u32x4 raw = *(const u32x4*)(src + (size_t)tok * LDA + d);
;         const float* pp = pos + l * 64 + d;
;         const f32x4 p0 = *(const f32x4*)pp, p1 = *(const f32x4*)(pp + 4);
;         u32x4 ap;
;         ap.x = cvt_pk_bf16(bf_lo(raw.x) + p0[0], bf_hi(raw.x) + p0[1]);
;         ap.y = cvt_pk_bf16(bf_lo(raw.y) + p0[2], bf_hi(raw.y) + p0[3]);
;         ap.z = cvt_pk_bf16(bf_lo(raw.z) + p1[0], bf_hi(raw.z) + p1[1]);
;         ap.w = cvt_pk_bf16(bf_lo(raw.w) + p1[2], bf_hi(raw.w) + p1[3]);
;         const bf16x8 a = __builtin_bit_cast(bf16x8, ap);
; #pragma unroll
;         for (int nt = 0; nt < 16; ++nt) {
;             const bf16x8 bw = *(const bf16x8*)(w1t + (size_t)(nt * 16 + fr) * 2048 + kk * 32 + fq * 8);
;             acc[nt] = mfma16(bw, a, acc[nt]);
;         }
.LBB0_250:
	v_readfirstlane_b32 s98, v92
	v_readfirstlane_b32 s99, v93
	v_readfirstlane_b32 s100, v114
	s_mov_b32 s18, 0
	v_mbcnt_lo_u32_b32 v129, -1, 0
	v_mbcnt_hi_u32_b32 v129, -1, v129
	v_lshlrev_b32_e32 v129, 4, v129
	s_nop 3
	s_lshr_b32 s100, s100, 6
	s_lshl_b32 s101, s100, 10
	s_lshl_b32 s100, s100, 14
	s_sub_u32 s98, s98, s101
	s_subb_u32 s99, s99, 0
	s_add_u32 s98, s98, s100
	s_addc_u32 s99, s99, 0
	v_min_u32_e32 v117, 0xfff, v89
	v_mul_u32_u24_e32 v117, 0x880, v117
	v_lshlrev_b32_e32 v64, 1, v117
	s_nop 0
	v_lshl_add_u64 v[126:127], v[90:91], 0, v[64:65]
	global_load_dword v131, v[126:127], off
	v_add_u32_e32 v117, 1, v89
	v_min_u32_e32 v117, 0xfff, v117
	v_mul_u32_u24_e32 v117, 0x880, v117
	v_lshlrev_b32_e32 v64, 1, v117
	s_nop 0
	v_lshl_add_u64 v[126:127], v[90:91], 0, v[64:65]
	global_load_dword v131, v[126:127], off
	v_add_u32_e32 v117, 2, v89
	v_min_u32_e32 v117, 0xfff, v117
	v_mul_u32_u24_e32 v117, 0x880, v117
	v_lshlrev_b32_e32 v64, 1, v117
	s_nop 0
	v_lshl_add_u64 v[126:127], v[90:91], 0, v[64:65]
	global_load_dword v131, v[126:127], off
	v_add_u32_e32 v117, 3, v89
	v_min_u32_e32 v117, 0xfff, v117
	v_mul_u32_u24_e32 v117, 0x880, v117
	v_lshlrev_b32_e32 v64, 1, v117
	s_nop 0
	v_lshl_add_u64 v[126:127], v[90:91], 0, v[64:65]
	global_load_dword v131, v[126:127], off
	v_add_u32_e32 v117, 4, v89
	v_min_u32_e32 v117, 0xfff, v117
	v_mul_u32_u24_e32 v117, 0x880, v117
	v_lshlrev_b32_e32 v64, 1, v117
	s_nop 0
	v_lshl_add_u64 v[126:127], v[90:91], 0, v[64:65]
	global_load_dword v131, v[126:127], off
	v_add_u32_e32 v117, 5, v89
	v_min_u32_e32 v117, 0xfff, v117
	v_mul_u32_u24_e32 v117, 0x880, v117
	v_lshlrev_b32_e32 v64, 1, v117
	s_nop 0
	v_lshl_add_u64 v[126:127], v[90:91], 0, v[64:65]
	global_load_dword v131, v[126:127], off
	v_add_u32_e32 v117, 6, v89
	v_min_u32_e32 v117, 0xfff, v117
	v_mul_u32_u24_e32 v117, 0x880, v117
	v_lshlrev_b32_e32 v64, 1, v117
	s_nop 0
	v_lshl_add_u64 v[126:127], v[90:91], 0, v[64:65]
	global_load_dword v131, v[126:127], off
	v_add_u32_e32 v117, 7, v89
	v_min_u32_e32 v117, 0xfff, v117
	v_mul_u32_u24_e32 v117, 0x880, v117
	v_lshlrev_b32_e32 v64, 1, v117
	s_nop 0
	v_lshl_add_u64 v[126:127], v[90:91], 0, v[64:65]
	global_load_dword v131, v[126:127], off
	v_lshl_add_u64 v[110:111], v[96:97], 0, v[86:87]
	v_min_u32_e32 v117, 0xfff, v89
	v_mul_u32_u24_e32 v117, 0x880, v117
	global_load_dwordx4 v[166:169], v[110:111], off
	global_load_dwordx4 v[170:173], v[110:111], off offset:16
	v_lshlrev_b32_e32 v64, 1, v117
	s_nop 0
	v_lshl_add_u64 v[126:127], v[90:91], 0, v[64:65]
	global_load_dwordx4 v[162:165], v[126:127], off
	v_lshl_add_u64 v[110:111], v[94:95], 0, v[86:87]
	v_min_u32_e32 v117, 0xfff, v105
	v_mul_u32_u24_e32 v117, 0x880, v117
	global_load_dwordx4 v[246:249], v[110:111], off offset:128
	global_load_dwordx4 v[250:253], v[110:111], off offset:144
	v_lshlrev_b32_e32 v64, 1, v117
	s_nop 0
	v_lshl_add_u64 v[126:127], v[90:91], 0, v[64:65]
	global_load_dwordx4 v[174:177], v[126:127], off offset:64
	global_load_dwordx4 v[180:183], v129, s[98:99]
	s_add_u32 s100, s98, 0x10000
	s_addc_u32 s101, s99, 0
	global_load_dwordx4 v[184:187], v129, s[100:101]
	s_add_u32 s100, s98, 0x400
	s_addc_u32 s101, s99, 0
	global_load_dwordx4 v[188:191], v129, s[100:101]
	s_add_u32 s100, s98, 0x10400
	s_addc_u32 s101, s99, 0
	global_load_dwordx4 v[192:195], v129, s[100:101]
	s_add_u32 s100, s98, 0x20000
	s_addc_u32 s101, s99, 0
	global_load_dwordx4 v[196:199], v129, s[100:101]
	s_add_u32 s100, s98, 0x30000
	s_addc_u32 s101, s99, 0
	global_load_dwordx4 v[200:203], v129, s[100:101]
	s_add_u32 s100, s98, 0x20400
	s_addc_u32 s101, s99, 0
	global_load_dwordx4 v[204:207], v129, s[100:101]
	s_add_u32 s100, s98, 0x30400
	s_addc_u32 s101, s99, 0
	global_load_dwordx4 v[208:211], v129, s[100:101]
	s_add_u32 s100, s98, 0x40000
	s_addc_u32 s101, s99, 0
	global_load_dwordx4 v[212:215], v129, s[100:101]
	s_add_u32 s100, s98, 0x50000
	s_addc_u32 s101, s99, 0
	global_load_dwordx4 v[216:219], v129, s[100:101]
	s_add_u32 s100, s98, 0x40400
	s_addc_u32 s101, s99, 0
	global_load_dwordx4 v[220:223], v129, s[100:101]
	s_add_u32 s100, s98, 0x50400
	s_addc_u32 s101, s99, 0
	global_load_dwordx4 v[224:227], v129, s[100:101]
	s_add_u32 s100, s98, 0x60000
	s_addc_u32 s101, s99, 0
	global_load_dwordx4 v[228:231], v129, s[100:101]
	s_add_u32 s100, s98, 0x70000
	s_addc_u32 s101, s99, 0
	global_load_dwordx4 v[232:235], v129, s[100:101]
	s_add_u32 s100, s98, 0x60400
	s_addc_u32 s101, s99, 0
	global_load_dwordx4 v[236:239], v129, s[100:101]
	s_add_u32 s100, s98, 0x70400
	s_addc_u32 s101, s99, 0
	global_load_dwordx4 v[240:243], v129, s[100:101]
; __device__ __forceinline__ unsigned cvt_pk_bf16(float lo, float hi) { const f32x2_t f = {lo, hi}; return __builtin_bit_cast(unsigned, __builtin_convertvector(f, bf16x2_t)); }
; __device__ __forceinline__ float bf_lo(unsigned u) { return __uint_as_float(u << 16); }
; __device__ __forceinline__ float bf_hi(unsigned u) { return __uint_as_float(u & 0xffff0000u); }
; __device__ __forceinline__ f32x4 mfma16(bf16x8 a, bf16x8 b, f32x4 c) { return __builtin_amdgcn_mfma_f32_16x16x32_bf16(a, b, c, 0, 0, 0); }
; __device__ __forceinline__ void compress_task(const Params& p, int task, char* smem) {
;     ...
;     for (int kq = 0; kq < 16; ++kq) {
;         const int kk = w * 16 + kq, l = kk >> 1, d = (kk & 1) * 32 + fq * 8;
;         int tok = 16 * n + l; tok = tok < S ? tok : S - 1;
;         const u32x4 raw = *(const u32x4*)(src + (size_t)tok * LDA + d);
;         const float* pp = pos + l * 64 + d;
;         const f32x4 p0 = *(const f32x4*)pp, p1 = *(const f32x4*)(pp + 4);
;         u32x4 ap;
;         ap.x = cvt_pk_bf16(bf_lo(raw.x) + p0[0], bf_hi(raw.x) + p0[1]);
;         ap.y = cvt_pk_bf16(bf_lo(raw.y) + p0[2], bf_hi(raw.y) + p0[3]);
;         ap.z = cvt_pk_bf16(bf_lo(raw.z) + p1[0], bf_hi(raw.z) + p1[1]);
;         ap.w = cvt_pk_bf16(bf_lo(raw.w) + p1[2], bf_hi(raw.w) + p1[3]);
;         const bf16x8 a = __builtin_bit_cast(bf16x8, ap);
; #pragma unroll
;         for (int nt = 0; nt < 16; ++nt) {
;             const bf16x8 bw = *(const bf16x8*)(w1t + (size_t)(nt * 16 + fr) * 2048 + kk * 32 + fq * 8);
;             acc[nt] = mfma16(bw, a, acc[nt]);
;         }
.Lcp_loop:
	s_waitcnt vmcnt(16)
	v_lshlrev_b32_e32 v118, 16, v162
	v_and_b32_e32 v119, 0xffff0000, v162
	v_lshlrev_b32_e32 v120, 16, v163
	v_and_b32_e32 v121, 0xffff0000, v163
	v_lshlrev_b32_e32 v122, 16, v164
	v_and_b32_e32 v123, 0xffff0000, v164
	v_lshlrev_b32_e32 v124, 16, v165
	v_and_b32_e32 v125, 0xffff0000, v165
	v_pk_add_f32 v[118:119], v[166:167], v[118:119]
	v_pk_add_f32 v[120:121], v[168:169], v[120:121]
	v_pk_add_f32 v[122:123], v[170:171], v[122:123]
	v_pk_add_f32 v[124:125], v[172:173], v[124:125]
	v_cvt_pk_bf16_f32 v106, v118, v119
	v_cvt_pk_bf16_f32 v107, v120, v121
	v_cvt_pk_bf16_f32 v108, v122, v123
	v_cvt_pk_bf16_f32 v109, v124, v125
	v_lshlrev_b32_e32 v118, 16, v174
	v_and_b32_e32 v119, 0xffff0000, v174
	v_lshlrev_b32_e32 v120, 16, v175
	v_and_b32_e32 v121, 0xffff0000, v175
	v_lshlrev_b32_e32 v122, 16, v176
	v_and_b32_e32 v123, 0xffff0000, v176
	v_lshlrev_b32_e32 v124, 16, v177
	v_and_b32_e32 v125, 0xffff0000, v177
	v_pk_add_f32 v[118:119], v[246:247], v[118:119]
	v_pk_add_f32 v[120:121], v[248:249], v[120:121]
	v_pk_add_f32 v[122:123], v[250:251], v[122:123]
	v_pk_add_f32 v[124:125], v[252:253], v[124:125]
	v_cvt_pk_bf16_f32 v140, v118, v119
	v_cvt_pk_bf16_f32 v141, v120, v121
	v_cvt_pk_bf16_f32 v142, v122, v123
	v_cvt_pk_bf16_f32 v143, v124, v125
	v_add_u32_e32 v89, 1, v89
	v_add_u32_e32 v105, 1, v105
	v_lshl_add_u64 v[96:97], v[96:97], 0, s[14:15]
	v_lshl_add_u64 v[94:95], v[94:95], 0, s[14:15]
	v_lshl_add_u64 v[110:111], v[96:97], 0, v[86:87]
	v_min_u32_e32 v117, 0xfff, v89
	v_mul_u32_u24_e32 v117, 0x880, v117
	global_load_dwordx4 v[166:169], v[110:111], off
	global_load_dwordx4 v[170:173], v[110:111], off offset:16
	v_lshlrev_b32_e32 v64, 1, v117
	s_nop 0
	v_lshl_add_u64 v[126:127], v[90:91], 0, v[64:65]
	global_load_dwordx4 v[162:165], v[126:127], off
	v_lshl_add_u64 v[110:111], v[94:95], 0, v[86:87]
	v_min_u32_e32 v117, 0xfff, v105
	v_mul_u32_u24_e32 v117, 0x880, v117
	global_load_dwordx4 v[246:249], v[110:111], off offset:128
	global_load_dwordx4 v[250:253], v[110:111], off offset:144
	v_lshlrev_b32_e32 v64, 1, v117
	s_nop 0
	v_lshl_add_u64 v[126:127], v[90:91], 0, v[64:65]
	global_load_dwordx4 v[174:177], v[126:127], off offset:64
	s_waitcnt vmcnt(21)
	v_mfma_f32_16x16x32_bf16 v[60:63], v[180:183], v[106:109], v[60:63]
	s_add_u32 s100, s98, 0x80000
	s_addc_u32 s101, s99, 0
	global_load_dwordx4 v[180:183], v129, s[100:101]
	s_waitcnt vmcnt(21)
	v_mfma_f32_16x16x32_bf16 v[56:59], v[184:187], v[106:109], v[56:59]
	s_add_u32 s100, s98, 0x90000
	s_addc_u32 s101, s99, 0
	global_load_dwordx4 v[184:187], v129, s[100:101]
	s_waitcnt vmcnt(21)
	v_mfma_f32_16x16x32_bf16 v[60:63], v[188:191], v[140:143], v[60:63]
	s_add_u32 s100, s98, 0x80400
	s_addc_u32 s101, s99, 0
	global_load_dwordx4 v[188:191], v129, s[100:101]
	s_waitcnt vmcnt(21)
	v_mfma_f32_16x16x32_bf16 v[56:59], v[192:195], v[140:143], v[56:59]
	s_add_u32 s100, s98, 0x90400
	s_addc_u32 s101, s99, 0
	global_load_dwordx4 v[192:195], v129, s[100:101]
	s_waitcnt vmcnt(21)
	v_mfma_f32_16x16x32_bf16 v[52:55], v[196:199], v[106:109], v[52:55]
	s_add_u32 s100, s98, 0xa0000
	s_addc_u32 s101, s99, 0
	global_load_dwordx4 v[196:199], v129, s[100:101]
	s_waitcnt vmcnt(21)
	v_mfma_f32_16x16x32_bf16 v[48:51], v[200:203], v[106:109], v[48:51]
	s_add_u32 s100, s98, 0xb0000
	s_addc_u32 s101, s99, 0
	global_load_dwordx4 v[200:203], v129, s[100:101]
	s_waitcnt vmcnt(21)
	v_mfma_f32_16x16x32_bf16 v[52:55], v[204:207], v[140:143], v[52:55]
	s_add_u32 s100, s98, 0xa0400
	s_addc_u32 s101, s99, 0
	global_load_dwordx4 v[204:207], v129, s[100:101]
	s_waitcnt vmcnt(21)
	v_mfma_f32_16x16x32_bf16 v[48:51], v[208:211], v[140:143], v[48:51]
	s_add_u32 s100, s98, 0xb0400
	s_addc_u32 s101, s99, 0
	global_load_dwordx4 v[208:211], v129, s[100:101]
	s_waitcnt vmcnt(21)
	v_mfma_f32_16x16x32_bf16 v[44:47], v[212:215], v[106:109], v[44:47]
	s_add_u32 s100, s98, 0xc0000
	s_addc_u32 s101, s99, 0
	global_load_dwordx4 v[212:215], v129, s[100:101]
	s_waitcnt vmcnt(21)
	v_mfma_f32_16x16x32_bf16 v[40:43], v[216:219], v[106:109], v[40:43]
	s_add_u32 s100, s98, 0xd0000
	s_addc_u32 s101, s99, 0
	global_load_dwordx4 v[216:219], v129, s[100:101]
	s_waitcnt vmcnt(21)
	v_mfma_f32_16x16x32_bf16 v[44:47], v[220:223], v[140:143], v[44:47]
	s_add_u32 s100, s98, 0xc0400
	s_addc_u32 s101, s99, 0
	global_load_dwordx4 v[220:223], v129, s[100:101]
	s_waitcnt vmcnt(21)
	v_mfma_f32_16x16x32_bf16 v[40:43], v[224:227], v[140:143], v[40:43]
	s_add_u32 s100, s98, 0xd0400
	s_addc_u32 s101, s99, 0
	global_load_dwordx4 v[224:227], v129, s[100:101]
	s_waitcnt vmcnt(21)
	v_mfma_f32_16x16x32_bf16 v[36:39], v[228:231], v[106:109], v[36:39]
	s_add_u32 s100, s98, 0xe0000
	s_addc_u32 s101, s99, 0
	global_load_dwordx4 v[228:231], v129, s[100:101]
	s_waitcnt vmcnt(21)
	v_mfma_f32_16x16x32_bf16 v[32:35], v[232:235], v[106:109], v[32:35]
	s_add_u32 s100, s98, 0xf0000
	s_addc_u32 s101, s99, 0
	global_load_dwordx4 v[232:235], v129, s[100:101]
	s_waitcnt vmcnt(21)
	v_mfma_f32_16x16x32_bf16 v[36:39], v[236:239], v[140:143], v[36:39]
	s_add_u32 s100, s98, 0xe0400
	s_addc_u32 s101, s99, 0
	global_load_dwordx4 v[236:239], v129, s[100:101]
	s_waitcnt vmcnt(21)
	v_mfma_f32_16x16x32_bf16 v[32:35], v[240:243], v[140:143], v[32:35]
	s_add_u32 s100, s98, 0xf0400
	s_addc_u32 s101, s99, 0
	global_load_dwordx4 v[240:243], v129, s[100:101]
	s_add_u32 s98, s98, 0x800
	s_addc_u32 s99, s99, 0
	s_waitcnt vmcnt(15)
	v_mfma_f32_16x16x32_bf16 v[28:31], v[180:183], v[106:109], v[28:31]
	global_load_dwordx4 v[180:183], v129, s[98:99]
	s_waitcnt vmcnt(15)
	v_mfma_f32_16x16x32_bf16 v[24:27], v[184:187], v[106:109], v[24:27]
	s_add_u32 s100, s98, 0x10000
	s_addc_u32 s101, s99, 0
	global_load_dwordx4 v[184:187], v129, s[100:101]
	s_waitcnt vmcnt(15)
; __device__ __forceinline__ f32x4 mfma16(bf16x8 a, bf16x8 b, f32x4 c) { return __builtin_amdgcn_mfma_f32_16x16x32_bf16(a, b, c, 0, 0, 0); }
; __device__ __forceinline__ void compress_task(const Params& p, int task, char* smem) {
;     ...
; #pragma unroll
;         for (int nt = 0; nt < 16; ++nt) {
;             const bf16x8 bw = *(const bf16x8*)(w1t + (size_t)(nt * 16 + fr) * 2048 + kk * 32 + fq * 8);
;             acc[nt] = mfma16(bw, a, acc[nt]);
;         }
	v_mfma_f32_16x16x32_bf16 v[28:31], v[188:191], v[140:143], v[28:31]
	s_add_u32 s100, s98, 0x400
	s_addc_u32 s101, s99, 0
	global_load_dwordx4 v[188:191], v129, s[100:101]
	s_waitcnt vmcnt(15)
	v_mfma_f32_16x16x32_bf16 v[24:27], v[192:195], v[140:143], v[24:27]
	s_add_u32 s100, s98, 0x10400
	s_addc_u32 s101, s99, 0
	global_load_dwordx4 v[192:195], v129, s[100:101]
	s_waitcnt vmcnt(15)
	v_mfma_f32_16x16x32_bf16 v[20:23], v[196:199], v[106:109], v[20:23]
	s_add_u32 s100, s98, 0x20000
	s_addc_u32 s101, s99, 0
	global_load_dwordx4 v[196:199], v129, s[100:101]
	s_waitcnt vmcnt(15)
	v_mfma_f32_16x16x32_bf16 v[16:19], v[200:203], v[106:109], v[16:19]
	s_add_u32 s100, s98, 0x30000
	s_addc_u32 s101, s99, 0
	global_load_dwordx4 v[200:203], v129, s[100:101]
	s_waitcnt vmcnt(15)
	v_mfma_f32_16x16x32_bf16 v[20:23], v[204:207], v[140:143], v[20:23]
	s_add_u32 s100, s98, 0x20400
	s_addc_u32 s101, s99, 0
	global_load_dwordx4 v[204:207], v129, s[100:101]
	s_waitcnt vmcnt(15)
	v_mfma_f32_16x16x32_bf16 v[16:19], v[208:211], v[140:143], v[16:19]
	s_add_u32 s100, s98, 0x30400
	s_addc_u32 s101, s99, 0
	global_load_dwordx4 v[208:211], v129, s[100:101]
	s_waitcnt vmcnt(15)
	v_mfma_f32_16x16x32_bf16 v[12:15], v[212:215], v[106:109], v[12:15]
	s_add_u32 s100, s98, 0x40000
	s_addc_u32 s101, s99, 0
	global_load_dwordx4 v[212:215], v129, s[100:101]
	s_waitcnt vmcnt(15)
	v_mfma_f32_16x16x32_bf16 v[8:11], v[216:219], v[106:109], v[8:11]
	s_add_u32 s100, s98, 0x50000
	s_addc_u32 s101, s99, 0
	global_load_dwordx4 v[216:219], v129, s[100:101]
	s_waitcnt vmcnt(15)
	v_mfma_f32_16x16x32_bf16 v[12:15], v[220:223], v[140:143], v[12:15]
	s_add_u32 s100, s98, 0x40400
	s_addc_u32 s101, s99, 0
	global_load_dwordx4 v[220:223], v129, s[100:101]
	s_waitcnt vmcnt(15)
	v_mfma_f32_16x16x32_bf16 v[8:11], v[224:227], v[140:143], v[8:11]
	s_add_u32 s100, s98, 0x50400
	s_addc_u32 s101, s99, 0
	global_load_dwordx4 v[224:227], v129, s[100:101]
	s_waitcnt vmcnt(15)
	v_mfma_f32_16x16x32_bf16 v[4:7], v[228:231], v[106:109], v[4:7]
	s_add_u32 s100, s98, 0x60000
	s_addc_u32 s101, s99, 0
	global_load_dwordx4 v[228:231], v129, s[100:101]
	s_waitcnt vmcnt(15)
	v_mfma_f32_16x16x32_bf16 v[0:3], v[232:235], v[106:109], v[0:3]
	s_add_u32 s100, s98, 0x70000
	s_addc_u32 s101, s99, 0
	global_load_dwordx4 v[232:235], v129, s[100:101]
	s_waitcnt vmcnt(15)
	v_mfma_f32_16x16x32_bf16 v[4:7], v[236:239], v[140:143], v[4:7]
	s_add_u32 s100, s98, 0x60400
	s_addc_u32 s101, s99, 0
	global_load_dwordx4 v[236:239], v129, s[100:101]
	s_waitcnt vmcnt(15)
	v_mfma_f32_16x16x32_bf16 v[0:3], v[240:243], v[140:143], v[0:3]
	s_add_u32 s100, s98, 0x70400
	s_addc_u32 s101, s99, 0
	global_load_dwordx4 v[240:243], v129, s[100:101]
	s_add_i32 s18, s18, 1
	s_cmp_lt_u32 s18, 7
	s_cbranch_scc1 .Lcp_loop
; __device__ __forceinline__ unsigned cvt_pk_bf16(float lo, float hi) { const f32x2_t f = {lo, hi}; return __builtin_bit_cast(unsigned, __builtin_convertvector(f, bf16x2_t)); }
; __device__ __forceinline__ float bf_lo(unsigned u) { return __uint_as_float(u << 16); }
; __device__ __forceinline__ float bf_hi(unsigned u) { return __uint_as_float(u & 0xffff0000u); }
; __device__ __forceinline__ f32x4 mfma16(bf16x8 a, bf16x8 b, f32x4 c) { return __builtin_amdgcn_mfma_f32_16x16x32_bf16(a, b, c, 0, 0, 0); }
; __device__ __forceinline__ void compress_task(const Params& p, int task, char* smem) {
;     ...
;     for (int kq = 0; kq < 16; ++kq) {
;         const int kk = w * 16 + kq, l = kk >> 1, d = (kk & 1) * 32 + fq * 8;
;         int tok = 16 * n + l; tok = tok < S ? tok : S - 1;
;         const u32x4 raw = *(const u32x4*)(src + (size_t)tok * LDA + d);
;         const float* pp = pos + l * 64 + d;
;         const f32x4 p0 = *(const f32x4*)pp, p1 = *(const f32x4*)(pp + 4);
;         u32x4 ap;
;         ap.x = cvt_pk_bf16(bf_lo(raw.x) + p0[0], bf_hi(raw.x) + p0[1]);
;         ap.y = cvt_pk_bf16(bf_lo(raw.y) + p0[2], bf_hi(raw.y) + p0[3]);
;         ap.z = cvt_pk_bf16(bf_lo(raw.z) + p1[0], bf_hi(raw.z) + p1[1]);
;         ap.w = cvt_pk_bf16(bf_lo(raw.w) + p1[2], bf_hi(raw.w) + p1[3]);
;         const bf16x8 a = __builtin_bit_cast(bf16x8, ap);
; #pragma unroll
;         for (int nt = 0; nt < 16; ++nt) {
;             const bf16x8 bw = *(const bf16x8*)(w1t + (size_t)(nt * 16 + fr) * 2048 + kk * 32 + fq * 8);
;             acc[nt] = mfma16(bw, a, acc[nt]);
;         }
;     }
;     float* red = (float*)smem;
;     bf16_t* hid = (bf16_t*)(smem + 49920);
;     if (w > 0) {
; #pragma unroll
;         for (int nt = 0; nt < 16; ++nt) *(f32x4*)(red + ((w - 1) * 16 + fr) * 260 + nt * 16 + fq * 4) = acc[nt];
;     }
	s_waitcnt vmcnt(16)
	v_lshlrev_b32_e32 v118, 16, v162
	v_and_b32_e32 v119, 0xffff0000, v162
	v_lshlrev_b32_e32 v120, 16, v163
	v_and_b32_e32 v121, 0xffff0000, v163
	v_lshlrev_b32_e32 v122, 16, v164
	v_and_b32_e32 v123, 0xffff0000, v164
	v_lshlrev_b32_e32 v124, 16, v165
	v_and_b32_e32 v125, 0xffff0000, v165
	v_pk_add_f32 v[118:119], v[166:167], v[118:119]
	v_pk_add_f32 v[120:121], v[168:169], v[120:121]
	v_pk_add_f32 v[122:123], v[170:171], v[122:123]
	v_pk_add_f32 v[124:125], v[172:173], v[124:125]
	v_cvt_pk_bf16_f32 v106, v118, v119
	v_cvt_pk_bf16_f32 v107, v120, v121
	v_cvt_pk_bf16_f32 v108, v122, v123
	v_cvt_pk_bf16_f32 v109, v124, v125
	v_lshlrev_b32_e32 v118, 16, v174
	v_and_b32_e32 v119, 0xffff0000, v174
	v_lshlrev_b32_e32 v120, 16, v175
	v_and_b32_e32 v121, 0xffff0000, v175
	v_lshlrev_b32_e32 v122, 16, v176
	v_and_b32_e32 v123, 0xffff0000, v176
	v_lshlrev_b32_e32 v124, 16, v177
	v_and_b32_e32 v125, 0xffff0000, v177
	v_pk_add_f32 v[118:119], v[246:247], v[118:119]
	v_pk_add_f32 v[120:121], v[248:249], v[120:121]
	v_pk_add_f32 v[122:123], v[250:251], v[122:123]
	v_pk_add_f32 v[124:125], v[252:253], v[124:125]
	v_cvt_pk_bf16_f32 v140, v118, v119
	v_cvt_pk_bf16_f32 v141, v120, v121
	v_cvt_pk_bf16_f32 v142, v122, v123
	v_cvt_pk_bf16_f32 v143, v124, v125
	s_waitcnt vmcnt(15)
	v_mfma_f32_16x16x32_bf16 v[60:63], v[180:183], v[106:109], v[60:63]
	s_add_u32 s100, s98, 0x80000
	s_addc_u32 s101, s99, 0
	global_load_dwordx4 v[180:183], v129, s[100:101]
	s_waitcnt vmcnt(15)
	v_mfma_f32_16x16x32_bf16 v[56:59], v[184:187], v[106:109], v[56:59]
	s_add_u32 s100, s98, 0x90000
	s_addc_u32 s101, s99, 0
	global_load_dwordx4 v[184:187], v129, s[100:101]
	s_waitcnt vmcnt(15)
	v_mfma_f32_16x16x32_bf16 v[60:63], v[188:191], v[140:143], v[60:63]
	s_add_u32 s100, s98, 0x80400
	s_addc_u32 s101, s99, 0
	global_load_dwordx4 v[188:191], v129, s[100:101]
	s_waitcnt vmcnt(15)
	v_mfma_f32_16x16x32_bf16 v[56:59], v[192:195], v[140:143], v[56:59]
	s_add_u32 s100, s98, 0x90400
	s_addc_u32 s101, s99, 0
	global_load_dwordx4 v[192:195], v129, s[100:101]
	s_waitcnt vmcnt(15)
	v_mfma_f32_16x16x32_bf16 v[52:55], v[196:199], v[106:109], v[52:55]
	s_add_u32 s100, s98, 0xa0000
	s_addc_u32 s101, s99, 0
	global_load_dwordx4 v[196:199], v129, s[100:101]
	s_waitcnt vmcnt(15)
	v_mfma_f32_16x16x32_bf16 v[48:51], v[200:203], v[106:109], v[48:51]
	s_add_u32 s100, s98, 0xb0000
	s_addc_u32 s101, s99, 0
	global_load_dwordx4 v[200:203], v129, s[100:101]
	s_waitcnt vmcnt(15)
	v_mfma_f32_16x16x32_bf16 v[52:55], v[204:207], v[140:143], v[52:55]
	s_add_u32 s100, s98, 0xa0400
	s_addc_u32 s101, s99, 0
	global_load_dwordx4 v[204:207], v129, s[100:101]
	s_waitcnt vmcnt(15)
	v_mfma_f32_16x16x32_bf16 v[48:51], v[208:211], v[140:143], v[48:51]
	s_add_u32 s100, s98, 0xb0400
	s_addc_u32 s101, s99, 0
	global_load_dwordx4 v[208:211], v129, s[100:101]
	s_waitcnt vmcnt(15)
	v_mfma_f32_16x16x32_bf16 v[44:47], v[212:215], v[106:109], v[44:47]
	s_add_u32 s100, s98, 0xc0000
	s_addc_u32 s101, s99, 0
	global_load_dwordx4 v[212:215], v129, s[100:101]
	s_waitcnt vmcnt(15)
	v_mfma_f32_16x16x32_bf16 v[40:43], v[216:219], v[106:109], v[40:43]
	s_add_u32 s100, s98, 0xd0000
	s_addc_u32 s101, s99, 0
	global_load_dwordx4 v[216:219], v129, s[100:101]
	s_waitcnt vmcnt(15)
	v_mfma_f32_16x16x32_bf16 v[44:47], v[220:223], v[140:143], v[44:47]
	s_add_u32 s100, s98, 0xc0400
	s_addc_u32 s101, s99, 0
	global_load_dwordx4 v[220:223], v129, s[100:101]
	s_waitcnt vmcnt(15)
	v_mfma_f32_16x16x32_bf16 v[40:43], v[224:227], v[140:143], v[40:43]
	s_add_u32 s100, s98, 0xd0400
	s_addc_u32 s101, s99, 0
	global_load_dwordx4 v[224:227], v129, s[100:101]
	s_waitcnt vmcnt(15)
	v_mfma_f32_16x16x32_bf16 v[36:39], v[228:231], v[106:109], v[36:39]
	s_add_u32 s100, s98, 0xe0000
	s_addc_u32 s101, s99, 0
	global_load_dwordx4 v[228:231], v129, s[100:101]
	s_waitcnt vmcnt(15)
	v_mfma_f32_16x16x32_bf16 v[32:35], v[232:235], v[106:109], v[32:35]
	s_add_u32 s100, s98, 0xf0000
	s_addc_u32 s101, s99, 0
	global_load_dwordx4 v[232:235], v129, s[100:101]
	s_waitcnt vmcnt(15)
	v_mfma_f32_16x16x32_bf16 v[36:39], v[236:239], v[140:143], v[36:39]
	s_add_u32 s100, s98, 0xe0400
	s_addc_u32 s101, s99, 0
	global_load_dwordx4 v[236:239], v129, s[100:101]
	s_waitcnt vmcnt(15)
	v_mfma_f32_16x16x32_bf16 v[32:35], v[240:243], v[140:143], v[32:35]
	s_add_u32 s100, s98, 0xf0400
	s_addc_u32 s101, s99, 0
	global_load_dwordx4 v[240:243], v129, s[100:101]
	s_waitcnt vmcnt(15)
	v_mfma_f32_16x16x32_bf16 v[28:31], v[180:183], v[106:109], v[28:31]
	s_waitcnt vmcnt(14)
	v_mfma_f32_16x16x32_bf16 v[24:27], v[184:187], v[106:109], v[24:27]
	s_waitcnt vmcnt(13)
	v_mfma_f32_16x16x32_bf16 v[28:31], v[188:191], v[140:143], v[28:31]
	s_waitcnt vmcnt(12)
	v_mfma_f32_16x16x32_bf16 v[24:27], v[192:195], v[140:143], v[24:27]
	s_waitcnt vmcnt(11)
	v_mfma_f32_16x16x32_bf16 v[20:23], v[196:199], v[106:109], v[20:23]
	s_waitcnt vmcnt(10)
	v_mfma_f32_16x16x32_bf16 v[16:19], v[200:203], v[106:109], v[16:19]
	s_waitcnt vmcnt(9)
	v_mfma_f32_16x16x32_bf16 v[20:23], v[204:207], v[140:143], v[20:23]
	s_waitcnt vmcnt(8)
	v_mfma_f32_16x16x32_bf16 v[16:19], v[208:211], v[140:143], v[16:19]
	s_waitcnt vmcnt(7)
	v_mfma_f32_16x16x32_bf16 v[12:15], v[212:215], v[106:109], v[12:15]
	s_waitcnt vmcnt(6)
	v_mfma_f32_16x16x32_bf16 v[8:11], v[216:219], v[106:109], v[8:11]
	s_waitcnt vmcnt(5)
	v_mfma_f32_16x16x32_bf16 v[12:15], v[220:223], v[140:143], v[12:15]
	s_waitcnt vmcnt(4)
	v_mfma_f32_16x16x32_bf16 v[8:11], v[224:227], v[140:143], v[8:11]
	s_waitcnt vmcnt(3)
	v_mfma_f32_16x16x32_bf16 v[4:7], v[228:231], v[106:109], v[4:7]
	s_waitcnt vmcnt(2)
	v_mfma_f32_16x16x32_bf16 v[0:3], v[232:235], v[106:109], v[0:3]
	s_waitcnt vmcnt(1)
	v_mfma_f32_16x16x32_bf16 v[4:7], v[236:239], v[140:143], v[4:7]
	s_waitcnt vmcnt(0)
	v_mfma_f32_16x16x32_bf16 v[0:3], v[240:243], v[140:143], v[0:3]
	s_and_saveexec_b64 s[18:19], s[6:7]
	s_cbranch_execz .LBB0_253
	ds_write_b128 v99, v[60:63]
	ds_write_b128 v99, v[56:59] offset:64
	ds_write_b128 v99, v[52:55] offset:128
	ds_write_b128 v99, v[48:51] offset:192
	ds_write_b128 v99, v[44:47] offset:256
	ds_write_b128 v99, v[40:43] offset:320
	ds_write_b128 v99, v[36:39] offset:384
	ds_write_b128 v99, v[32:35] offset:448
	ds_write_b128 v99, v[28:31] offset:512
	ds_write_b128 v99, v[24:27] offset:576
	ds_write_b128 v99, v[20:23] offset:640
	ds_write_b128 v99, v[16:19] offset:704
	ds_write_b128 v99, v[12:15] offset:768
	ds_write_b128 v99, v[8:11] offset:832
	ds_write_b128 v99, v[4:7] offset:896
	ds_write_b128 v99, v[0:3] offset:960
